# SwiGLU epilogue stores deferred into next unit K-loop load segments (7 register-held + 1 LDS-held per wave)
# speedup vs baseline: 1.0099x; 1.0023x over previous
; #define PG8_STAGE(bufoff, gbase, voff) do { _Pragma("unroll") for (int _i = 0; _i < 2; ++_i) \
;         __builtin_amdgcn_global_load_lds((const unsigned*)((const char*)(gbase) + (voff)[_i]), (PG8_LAS unsigned*)(lds + (bufoff) + ldsw + _i * 8192), 16, 0, 0); } while (0)
; #define PG8_WAIT_V(n) asm volatile("s_waitcnt vmcnt(" #n ")" ::: "memory")
; #define PG8_BAR __builtin_amdgcn_s_barrier()
; template <class Epi, class Sched, bool ALIGN_EPI = false, bool SP2 = false>
; __device__ __forceinline__ void gemm_phase(PG8_LAS unsigned char* lds, const Gemm g, const Sched& S, const Epi& E) {
;     ...
;         PG8_STAGE(PG8_SB(0, 0), cB, voffB); PG8_STAGE(PG8_SB(0, 1), cB + hstepB, voffB); PG8_STAGE(PG8_SA(0, 0), cA, voffA); PG8_STAGE(PG8_SA(0, 1), cA + hstepA, voffA);
;         if (wr == 1) PG8_BAR;
;         PG8_WAIT_V(2); PG8_BAR;
;         PG8_STAGE(PG8_SB(1, 0), cB + kstep, voffB); PG8_STAGE(PG8_SA(1, 0), cA + kstep, voffA); PG8_STAGE(PG8_SB(1, 1), cB + hstepB + kstep, voffB);
;         PG8_WAIT_V(6); PG8_BAR;
;     __device__ __forceinline__ void operator()(const pg8::f32x4 (&acc)[2][2][4][2], const Unit& u, int wr, int wc, int fr, int fq) const {
;         const int row0 = u.pm * BM + wr * 64 + fr, col0 = u.pn * HALF + wc * 32 + 8 * fq;
;         float rsv[8]; rstd8(ss, row0, fq, rsv);
.LBB0_685:
	s_add_u32 s8, s78, 0x13c00000
	s_addc_u32 s9, s79, 0
	s_lshl_b32 s10, s10, 5
	s_and_b32 s16, s10, 0x60
	s_mov_b64 s[10:11], 0x80
	s_add_i32 m0, s23, 0x18000
	v_lshl_add_u64 v[8:9], v[8:9], 0, s[10:11]
	s_lshl_b32 s13, s12, 13
	s_lshl_b32 s17, s16, 7
	s_waitcnt vmcnt(2)
	s_barrier
	global_load_lds_dwordx4 v[8:9], off
	v_lshl_add_u64 v[6:7], v[6:7], 0, s[10:11]
	s_add_i32 m0, s23, 0x1a000
	s_add_i32 s38, s23, 0x8000
	s_add_i32 s39, s23, 0xa000
	global_load_lds_dwordx4 v[6:7], off
	v_lshl_add_u64 v[2:3], v[2:3], 0, s[10:11]
	s_mov_b32 m0, s38
	s_add_u32 s14, s26, 0x40080
	global_load_lds_dwordx4 v[2:3], off
	v_lshl_add_u64 v[2:3], v[4:5], 0, s[10:11]
	s_mov_b32 m0, s39
	s_addc_u32 s15, s27, 0
	global_load_lds_dwordx4 v[2:3], off
	s_add_i32 m0, s23, 0x1c000
	v_lshl_add_u64 v[2:3], s[14:15], 0, v[134:135]
	global_load_lds_dwordx4 v[2:3], off
	v_lshl_add_u64 v[2:3], s[14:15], 0, v[130:131]
	s_add_i32 m0, s23, 0x1e000
	v_bfe_u32 v4, v12, 4, 2
	global_load_lds_dwordx4 v[2:3], off
	v_and_b32_e32 v3, 15, v12
	v_lshlrev_b32_e32 v2, 4, v4
	v_lshlrev_b32_e32 v5, 2, v12
	v_lshl_or_b32 v1, s12, 6, v3
	v_lshl_or_b32 v3, v3, 6, v2
	v_and_b32_e32 v5, 32, v5
	v_bitop3_b32 v6, v3, s13, v5 bitop3:0xde
	v_bitop3_b32 v166, v3, s17, v5 bitop3:0xde
	v_mov_b32_e32 v3, v135
	s_sext_i32_i8 s45, s6
	s_cmpk_lt_u32 s7, 0x100
	v_lshl_add_u64 v[2:3], s[78:79], 0, v[2:3]
	s_mov_b64 s[6:7], 0x5a00000
	v_lshl_add_u64 v[138:139], v[2:3], 0, s[6:7]
	v_lshlrev_b32_e32 v2, 14, v15
	v_and_b32_e32 v2, 0xffff8000, v2
	v_lshl_add_u32 v2, v14, 11, v2
	v_and_b32_e32 v3, 1, v15
	v_lshl_or_b32 v2, v3, 6, v2
	v_lshl_add_u32 v140, v16, 1, v2
	v_lshlrev_b32_e32 v2, 14, v10
	v_and_b32_e32 v2, 0xffff8000, v2
	v_lshl_add_u32 v2, v11, 11, v2
	v_and_b32_e32 v3, 1, v10
	s_waitcnt vmcnt(6)
	v_lshl_or_b32 v2, v3, 6, v2
	s_cselect_b64 s[12:13], -1, 0
	v_lshl_add_u32 v142, v13, 1, v2
	s_add_i32 s42, 0, 0x10000
	s_add_i32 s43, 0, 0x14000
	v_mbcnt_lo_u32_b32 v2, -1, 0
	s_ashr_i32 s40, s82, 31
	s_mov_b32 s41, s82
	v_lshl_or_b32 v167, v4, 3, s16
	v_mul_u32_u24_e32 v255, 0x1600, v1
	v_lshl_add_u32 v255, v167, 1, v255
	s_mov_b32 s99, 0
	v_mov_b32_e32 v141, v135
	v_mov_b32_e32 v143, v135
	v_add_u32_e32 v168, s42, v166
	v_add_u32_e32 v169, s43, v166
	v_add_u32_e32 v170, 0, v6
	v_mbcnt_hi_u32_b32 v171, -1, v2
	v_mov_b32_e32 v172, 0x358637bd
	s_movk_i32 s44, 0x1600
	s_barrier
	s_branch .LBB0_688

;     __device__ __forceinline__ bool next(int i, Unit& u) const { const int L = i * G + c; if (L >= nM * nN * ng) return false; const int per = nM * nN, r = L % per; u.g = L / per; u.pn = r / nM; u.pm = r % nM; return true; }
;     __host__ __device__ bool next(int i, Unit& u) const {
;         const long L = (long)i * G + c; if (L >= nwg) return false;
;         int wgid = (int)L; { const int q = nwg / NXCD, r = nwg % NXCD, xcd = wgid % NXCD, off = wgid / NXCD; wgid = (xcd < r ? xcd * (q + 1) : r * (q + 1) + (xcd - r) * q) + off; }
;         const int nig = WGM * nN, gid = wgid / nig, fm = gid * WGM, gsz = (nM - fm) < WGM ? (nM - fm) : WGM;
;         u.pm = fm + ((wgid % nig) % gsz); u.pn = (wgid % nig) / gsz; u.g = 0; return true;
; template <class Epi, class Sched, bool ALIGN_EPI = false, bool SP2 = false>
; __device__ __forceinline__ void gemm_phase(PG8_LAS unsigned char* lds, const Gemm g, const Sched& S, const Epi& E) {
;     ...
;         const bool has_next = S.next(ui + 1, nxt);
.LBB0_688:
	s_add_i32 s37, s37, 1
	s_mul_i32 s6, s37, s40
	s_mul_hi_u32 s7, s37, s41
	s_add_i32 s7, s7, s6
	s_mul_i32 s6, s37, s41
	s_add_u32 s18, s6, s96
	s_addc_u32 s19, s7, s31
	s_cmp_gt_i32 s18, 0xaff
	s_cselect_b64 vcc, -1, 0
	s_cmp_lt_i32 s18, 0xb00
	s_cselect_b64 s[6:7], -1, 0
	s_cbranch_vccnz .LBB0_690
	s_ashr_i32 s14, s18, 31
	s_lshr_b32 s14, s14, 29
	s_add_i32 s14, s18, s14
	s_ashr_i32 s15, s14, 3
	s_and_b32 s14, s14, -8
	s_sub_i32 s14, s18, s14
	s_cmp_lt_i32 s14, 0
	s_cselect_b32 s16, s33, 0x160
	s_mul_i32 s14, s14, s16
	s_add_i32 s14, s14, s15
	s_mul_hi_i32 s15, s14, 0x2e8ba2e9
	s_lshr_b32 s16, s15, 31
	s_ashr_i32 s15, s15, 4
	s_add_i32 s15, s15, s16
	s_lshl_b32 s16, s15, 2
	s_sub_i32 s17, 0x80, s16
	s_min_i32 s17, s17, 4
	s_abs_i32 s18, s17
	v_cvt_f32_u32_e32 v2, s18
	s_sub_i32 s20, 0, s18
	s_mulk_i32 s15, 0x58
	s_sub_i32 s15, s14, s15
	v_rcp_iflag_f32_e32 v2, v2
	s_abs_i32 s14, s15
	s_xor_b32 s19, s15, s17
	s_ashr_i32 s19, s19, 31
	v_mul_f32_e32 v2, 0x4f7ffffe, v2
	v_cvt_u32_f32_e32 v2, v2
	s_nop 0
	v_readfirstlane_b32 s21, v2
	s_mul_i32 s20, s20, s21
	s_mul_hi_u32 s20, s21, s20
	s_add_i32 s21, s21, s20
	s_mul_hi_u32 s20, s14, s21
	s_mul_i32 s21, s20, s18
	s_sub_i32 s14, s14, s21
	s_add_i32 s28, s20, 1
	s_sub_i32 s21, s14, s18
	s_cmp_ge_u32 s14, s18
	s_cselect_b32 s20, s28, s20
	s_cselect_b32 s14, s21, s14
	s_add_i32 s21, s20, 1
	s_cmp_ge_u32 s14, s18
	s_cselect_b32 s14, s21, s20
	s_xor_b32 s14, s14, s19
	s_sub_i32 s14, s14, s19
	s_mul_i32 s17, s14, s17
	s_sub_i32 s15, s15, s17
	s_add_i32 s16, s16, s15

; #define PG8_STAGE(bufoff, gbase, voff) do { _Pragma("unroll") for (int _i = 0; _i < 2; ++_i) \
;         __builtin_amdgcn_global_load_lds((const unsigned*)((const char*)(gbase) + (voff)[_i]), (PG8_LAS unsigned*)(lds + (bufoff) + ldsw + _i * 8192), 16, 0, 0); } while (0)
; #define PG8_LDA(dst, b, h) do { _Pragma("unroll") for (int m = 0; m < 4; ++m) _Pragma("unroll") for (int k = 0; k < 2; ++k) dst[m][k] = *(const PG8_LAS bf16x8*)(lds + PG8_SA(b, h) + aoff + m * 2048 + k * 1024); } while (0)
; #define PG8_LDB(dst, b, h) do { _Pragma("unroll") for (int n = 0; n < 2; ++n) _Pragma("unroll") for (int k = 0; k < 2; ++k) dst[n][k] = *(const PG8_LAS bf16x8*)(lds + PG8_SB(b, h) + boff + n * 2048 + k * 1024); } while (0)
; #define PG8_SCHED __builtin_amdgcn_sched_barrier(0)
; template <class Epi, class Sched, bool ALIGN_EPI = false, bool SP2 = false>
; __device__ __forceinline__ void gemm_phase(PG8_LAS unsigned char* lds, const Gemm g, const Sched& S, const Epi& E) {
;     ...
;         for (int t = 0; t < nt; t += 2) {
;             const bool last = (t == nt - 2);
;             const char* a1 = cA + (size_t)(t + 1) * kstep;
;             const char* a2 = last ? nA : cA + (size_t)(t + 2) * kstep; const char* b2 = last ? nB : cB + (size_t)(t + 2) * kstep;
;             const char* a3 = a2 + kstep; const char* b3 = b2 + kstep;
;             if (last && has_next) S.a_ready(nxt);
;             if constexpr (SP2) {
;             PG8_LDB(B0, 0, 0); PG8_LDB(B1, 0, 1); PG8_SCHED; PG8_LDA(At, 0, 0); PG8_STAGE(PG8_SA(1, 1), a1 + hstepA, voffA);
;     __device__ __forceinline__ void operator()(const pg8::f32x4 (&acc)[2][2][4][2], const Unit& u, int wr, int wc, int fr, int fq) const {
;     ...
;                 __builtin_nontemporal_store(w, (v4u*)(O + (size_t)(row0 + ai * HALF + m * 16) * FF + col0)); }
.LBB0_691:
	s_cmp_eq_u32 s99, 0
	s_cbranch_scc1 .Ld7_done_0
	s_cmp_lt_i32 s50, 6
	s_cbranch_scc0 .Ld7_hi_0
	s_cmp_lt_i32 s50, 2
	s_cbranch_scc0 .Ld7_23_0
	s_cmp_lt_i32 s50, 0
	s_cbranch_scc0 .Ld7_1_0
	global_store_dwordx4 v255, v[230:233], s[98:99] nt
	s_branch .Ld7_done_0
.Ld7_1_0:
	s_add_u32 s100, s98, 0x16000
	s_addc_u32 s101, s99, 0
	global_store_dwordx4 v255, v[234:237], s[100:101] nt
	s_branch .Ld7_done_0
.Ld7_23_0:
	s_cmp_lt_i32 s50, 4
	s_cbranch_scc0 .Ld7_3_0
	s_add_u32 s100, s98, 0x2c000
	s_addc_u32 s101, s99, 0
	global_store_dwordx4 v255, v[238:241], s[100:101] nt
	s_branch .Ld7_done_0
.Ld7_3_0:
	s_add_u32 s100, s98, 0x42000
	s_addc_u32 s101, s99, 0
	global_store_dwordx4 v255, v[242:245], s[100:101] nt
	s_branch .Ld7_done_0
.Ld7_hi_0:
	s_cmp_lt_i32 s50, 10
	s_cbranch_scc0 .Ld7_67_0
	s_cmp_lt_i32 s50, 8
	s_cbranch_scc0 .Ld7_5_0
	s_add_u32 s100, s98, 0xb0000
	s_addc_u32 s101, s99, 0
	global_store_dwordx4 v255, v[246:249], s[100:101] nt
	s_branch .Ld7_done_0
.Ld7_5_0:
	s_add_u32 s100, s98, 0xc6000
	s_addc_u32 s101, s99, 0
	global_store_dwordx4 v255, v[250:253], s[100:101] nt
	s_branch .Ld7_done_0
.Ld7_67_0:
	s_cmp_lt_i32 s50, 12
	s_cbranch_scc0 .Ld7_7_0
	s_add_u32 s100, s98, 0xdc000
	s_addc_u32 s101, s99, 0
	global_store_dwordx4 v255, v[144:147], s[100:101] nt
	v_lshlrev_b32_e32 v230, 4, v171
	v_add_u32_e32 v230, s23, v230
	v_add_u32_e32 v230, 0x20100, v230
	ds_read_b128 v[230:233], v230
	s_branch .Ld7_done_0
.Ld7_7_0:
	s_add_u32 s100, s98, 0xf2000
	s_addc_u32 s101, s99, 0
	global_store_dwordx4 v255, v[230:233], s[100:101] nt

; __device__ __forceinline__ unsigned cvt_pk_bf16(float lo, float hi) { unsigned r; asm volatile("v_cvt_pk_bf16_f32 %0, %1, %2" : "=v"(r) : "v"(lo), "v"(hi)); return r; }
; __device__ __forceinline__ void rstd8(const float* ss, int row0, int fq, float (&rs)[8]) {
;     f32x4 a[8];
; #pragma unroll
;     for (int k = 0; k < 8; ++k) a[k] = *(const f32x4*)(ss + (size_t)(row0 + (k >> 2) * 128 + (k & 3) * 16) * 16 + 4 * fq);
; #pragma unroll
;     for (int k = 0; k < 8; ++k) { float s = (a[k][0] + a[k][1]) + (a[k][2] + a[k][3]); s += __shfl_xor(s, 16); s += __shfl_xor(s, 32); rs[k] = __builtin_amdgcn_rsqf(s * (1.f / 1024.f) + EPS); }
; }
;     __device__ __forceinline__ void operator()(const pg8::f32x4 (&acc)[2][2][4][2], const Unit& u, int wr, int wc, int fr, int fq) const {
;         const int row0 = u.pm * BM + wr * 64 + fr, col0 = u.pn * HALF + wc * 32 + 8 * fq;
;         float rsv[8]; rstd8(ss, row0, fq, rsv);
; #pragma unroll
;         for (int ai = 0; ai < 2; ++ai)
; #pragma unroll
;             for (int m = 0; m < 4; ++m) { float r[8]; const float rs = rsv[ai * 4 + m]; const float c1 = -1.4426950408889634f * rs, rs2 = rs * rs;
; #pragma unroll
;                 for (int n = 0; n < 2; ++n)
; #pragma unroll
;                     for (int e = 0; e < 4; e += 2) { const f32x2 ag = {acc[ai][0][m][n][e], acc[ai][0][m][n][e + 1]}, au = {acc[ai][1][m][n][e], acc[ai][1][m][n][e + 1]};
;                         const f32x2 t = ag * c1; f32x2 d; d.x = __builtin_amdgcn_exp2f(t.x); d.y = __builtin_amdgcn_exp2f(t.y); d = d + 1.0f;
;                         f32x2 q; q.x = __builtin_amdgcn_rcpf(d.x); q.y = __builtin_amdgcn_rcpf(d.y); const f32x2 o = (ag * au) * rs2 * q; r[4 * n + e] = o.x; r[4 * n + e + 1] = o.y; }
;                 v4u w; w.x = cvt_pk_bf16(r[0], r[1]); w.y = cvt_pk_bf16(r[2], r[3]); w.z = cvt_pk_bf16(r[4], r[5]); w.w = cvt_pk_bf16(r[6], r[7]);
;                 __builtin_nontemporal_store(w, (v4u*)(O + (size_t)(row0 + ai * HALF + m * 16) * FF + col0)); }
.LBB0_694:
	v_lshl_add_u32 v162, s22, 8, v1
	v_ashrrev_i32_e32 v163, 31, v162
	v_or_b32_e32 v160, 16, v162
	v_lshlrev_b64 v[148:149], 6, v[162:163]
	v_ashrrev_i32_e32 v161, 31, v160
	v_or_b32_e32 v158, 32, v162
	v_lshl_add_u64 v[148:149], v[138:139], 0, v[148:149]
	v_lshlrev_b64 v[150:151], 6, v[160:161]
	v_ashrrev_i32_e32 v159, 31, v158
	v_or_b32_e32 v156, 48, v162
	v_lshl_add_u64 v[150:151], v[138:139], 0, v[150:151]
	global_load_dwordx4 v[174:177], v[148:149], off
	global_load_dwordx4 v[178:181], v[150:151], off
	v_lshlrev_b64 v[148:149], 6, v[158:159]
	v_ashrrev_i32_e32 v157, 31, v156
	v_lshl_add_u64 v[148:149], v[138:139], 0, v[148:149]
	v_lshlrev_b64 v[150:151], 6, v[156:157]
	v_lshl_add_u64 v[150:151], v[138:139], 0, v[150:151]
	global_load_dwordx4 v[182:185], v[148:149], off
	global_load_dwordx4 v[186:189], v[150:151], off
	v_add_u32_e32 v154, 0x80, v162
	v_ashrrev_i32_e32 v155, 31, v154
	v_lshlrev_b64 v[148:149], 6, v[154:155]
	v_lshl_add_u64 v[148:149], v[138:139], 0, v[148:149]
	global_load_dwordx4 v[190:193], v[148:149], off
	v_add_u32_e32 v152, 0x90, v162
	v_ashrrev_i32_e32 v153, 31, v152
	v_lshlrev_b64 v[148:149], 6, v[152:153]
	v_add_u32_e32 v150, 0xa0, v162
	v_lshl_add_u64 v[148:149], v[138:139], 0, v[148:149]
	v_ashrrev_i32_e32 v151, 31, v150
	global_load_dwordx4 v[194:197], v[148:149], off
	v_lshlrev_b64 v[148:149], 6, v[150:151]
	v_lshl_add_u64 v[148:149], v[138:139], 0, v[148:149]
	global_load_dwordx4 v[198:201], v[148:149], off
	v_add_u32_e32 v148, 0xb0, v162
	v_ashrrev_i32_e32 v149, 31, v148
	v_lshlrev_b64 v[202:203], 6, v[148:149]
	v_lshl_add_u64 v[202:203], v[138:139], 0, v[202:203]
	global_load_dwordx4 v[202:205], v[202:203], off
	v_and_b32_e32 v151, 64, v171
	v_xor_b32_e32 v149, 16, v171
	v_add_u32_e32 v151, 64, v151
	v_xor_b32_e32 v153, 32, v171
	v_cmp_lt_i32_e32 vcc, v149, v151
	v_pk_mul_f32 v[124:125], v[128:129], v[124:125]
	v_pk_mul_f32 v[122:123], v[126:127], v[122:123]
	v_cndmask_b32_e32 v149, v171, v149, vcc
	v_cmp_lt_i32_e32 vcc, v153, v151
	v_lshlrev_b32_e32 v149, 2, v149
	v_pk_mul_f32 v[114:115], v[118:119], v[114:115]
	v_cndmask_b32_e32 v151, v171, v153, vcc
	v_lshlrev_b32_e32 v151, 2, v151
	v_pk_mul_f32 v[116:117], v[120:121], v[116:117]
	v_lshl_or_b32 v164, s45, 7, v167
	v_pk_mul_f32 v[108:109], v[112:113], v[108:109]
	v_pk_mul_f32 v[106:107], v[110:111], v[106:107]
	v_pk_mul_f32 v[98:99], v[102:103], v[98:99]
	v_pk_mul_f32 v[100:101], v[104:105], v[100:101]
	v_pk_mul_f32 v[92:93], v[96:97], v[92:93]
	v_pk_mul_f32 v[90:91], v[94:95], v[90:91]
	v_pk_mul_f32 v[82:83], v[86:87], v[82:83]
	v_pk_mul_f32 v[84:85], v[88:89], v[84:85]
	v_pk_mul_f32 v[76:77], v[80:81], v[76:77]
	v_pk_mul_f32 v[74:75], v[78:79], v[74:75]
	v_pk_mul_f32 v[66:67], v[70:71], v[66:67]
	v_pk_mul_f32 v[68:69], v[72:73], v[68:69]
	v_pk_mul_f32 v[60:61], v[64:65], v[60:61]
	v_pk_mul_f32 v[58:59], v[62:63], v[58:59]
	v_pk_mul_f32 v[50:51], v[54:55], v[50:51]
	v_pk_mul_f32 v[52:53], v[56:57], v[52:53]
	v_pk_mul_f32 v[44:45], v[48:49], v[44:45]
	v_pk_mul_f32 v[42:43], v[46:47], v[42:43]
	v_pk_mul_f32 v[34:35], v[38:39], v[34:35]
	v_pk_mul_f32 v[36:37], v[40:41], v[36:37]
	v_pk_mul_f32 v[28:29], v[32:33], v[28:29]
	v_pk_mul_f32 v[26:27], v[30:31], v[26:27]
	v_pk_mul_f32 v[18:19], v[22:23], v[18:19]
	v_pk_mul_f32 v[20:21], v[24:25], v[20:21]
	v_pk_mul_f32 v[12:13], v[16:17], v[12:13]
	v_pk_mul_f32 v[10:11], v[14:15], v[10:11]
	v_pk_mul_f32 v[2:3], v[6:7], v[2:3]
	v_pk_mul_f32 v[4:5], v[8:9], v[4:5]
	s_andn2_b64 vcc, exec, s[6:7]
	s_mov_b64 s[6:7], -1
	s_waitcnt vmcnt(0)
	v_mov_b32_e32 v206, v175
	v_mov_b32_e32 v207, v176
	v_mov_b32_e32 v175, v177
	v_pk_add_f32 v[174:175], v[206:207], v[174:175]
	v_mov_b32_e32 v176, v179
	v_mov_b32_e32 v177, v180
	v_mov_b32_e32 v179, v181
	v_mov_b32_e32 v180, v183
	v_mov_b32_e32 v181, v184
	v_mov_b32_e32 v183, v185
	v_mov_b32_e32 v184, v187
	v_mov_b32_e32 v185, v188
	v_mov_b32_e32 v187, v189
	v_add_f32_e32 v153, v174, v175
	v_pk_add_f32 v[174:175], v[176:177], v[178:179]
	v_pk_add_f32 v[176:177], v[180:181], v[182:183]
	v_pk_add_f32 v[178:179], v[184:185], v[186:187]
	v_add_f32_e32 v157, v174, v175
	v_add_f32_e32 v159, v176, v177
	v_add_f32_e32 v161, v178, v179
	ds_bpermute_b32 v155, v149, v153
	ds_bpermute_b32 v165, v149, v157
	ds_bpermute_b32 v173, v149, v159
	ds_bpermute_b32 v174, v149, v161
	v_mov_b32_e32 v188, v191
	v_mov_b32_e32 v189, v192
	v_mov_b32_e32 v191, v193
	v_pk_add_f32 v[180:181], v[188:189], v[190:191]
	s_waitcnt lgkmcnt(3)
	v_add_f32_e32 v153, v153, v155
	v_add_f32_e32 v163, v180, v181
	s_waitcnt lgkmcnt(2)
	v_add_f32_e32 v157, v157, v165
	s_waitcnt lgkmcnt(1)
	v_add_f32_e32 v159, v159, v173
	s_waitcnt lgkmcnt(0)
	v_add_f32_e32 v161, v161, v174
	ds_bpermute_b32 v175, v149, v163
	ds_bpermute_b32 v155, v151, v153
	ds_bpermute_b32 v165, v151, v157
	ds_bpermute_b32 v173, v151, v159
	ds_bpermute_b32 v174, v151, v161
	s_waitcnt lgkmcnt(4)
	v_add_f32_e32 v163, v163, v175
	s_waitcnt lgkmcnt(3)
	v_add_f32_e32 v153, v153, v155
	s_waitcnt lgkmcnt(2)
	v_add_f32_e32 v155, v157, v165
	s_waitcnt lgkmcnt(1)
	v_add_f32_e32 v157, v159, v173
	s_waitcnt lgkmcnt(0)
	v_add_f32_e32 v159, v161, v174
	v_mov_b32_e32 v174, v195
	v_mov_b32_e32 v175, v196
	v_mov_b32_e32 v195, v197
	v_pk_add_f32 v[174:175], v[174:175], v[194:195]
	ds_bpermute_b32 v176, v151, v163
	v_add_f32_e32 v161, v174, v175
	v_mov_b32_e32 v174, v199
	v_mov_b32_e32 v175, v200
	v_mov_b32_e32 v199, v201
	v_pk_add_f32 v[174:175], v[174:175], v[198:199]
	ds_bpermute_b32 v165, v149, v161
	v_add_f32_e32 v173, v174, v175
	v_mov_b32_e32 v174, v203
	v_mov_b32_e32 v175, v204
	v_mov_b32_e32 v203, v205
	v_pk_add_f32 v[174:175], v[174:175], v[202:203]
	s_waitcnt lgkmcnt(1)
; __device__ __forceinline__ unsigned cvt_pk_bf16(float lo, float hi) { unsigned r; asm volatile("v_cvt_pk_bf16_f32 %0, %1, %2" : "=v"(r) : "v"(lo), "v"(hi)); return r; }
;     __device__ __forceinline__ void operator()(const pg8::f32x4 (&acc)[2][2][4][2], const Unit& u, int wr, int wc, int fr, int fq) const {
;     ...
;             for (int m = 0; m < 4; ++m) { float r[8]; const float rs = rsv[ai * 4 + m]; const float c1 = -1.4426950408889634f * rs, rs2 = rs * rs;
; #pragma unroll
;                 for (int n = 0; n < 2; ++n)
; #pragma unroll
;                     for (int e = 0; e < 4; e += 2) { const f32x2 ag = {acc[ai][0][m][n][e], acc[ai][0][m][n][e + 1]}, au = {acc[ai][1][m][n][e], acc[ai][1][m][n][e + 1]};
;                         const f32x2 t = ag * c1; f32x2 d; d.x = __builtin_amdgcn_exp2f(t.x); d.y = __builtin_amdgcn_exp2f(t.y); d = d + 1.0f;
;                         f32x2 q; q.x = __builtin_amdgcn_rcpf(d.x); q.y = __builtin_amdgcn_rcpf(d.y); const f32x2 o = (ag * au) * rs2 * q; r[4 * n + e] = o.x; r[4 * n + e + 1] = o.y; }
;                 v4u w; w.x = cvt_pk_bf16(r[0], r[1]); w.y = cvt_pk_bf16(r[2], r[3]); w.z = cvt_pk_bf16(r[4], r[5]); w.w = cvt_pk_bf16(r[6], r[7]);
;                 __builtin_nontemporal_store(w, (v4u*)(O + (size_t)(row0 + ai * HALF + m * 16) * FF + col0)); }
	v_add_f32_e32 v163, v163, v176
	v_add_f32_e32 v174, v174, v175
	ds_bpermute_b32 v176, v149, v173
	ds_bpermute_b32 v149, v149, v174
	v_fmamk_f32 v153, v153, 0x3a800000, v172
	v_rsq_f32_e32 v153, v153
	s_waitcnt lgkmcnt(2)
	v_add_f32_e32 v161, v161, v165
	ds_bpermute_b32 v165, v151, v161
	s_waitcnt lgkmcnt(1)
	v_add_f32_e32 v149, v174, v149
	ds_bpermute_b32 v174, v151, v149
	v_mul_f32_e32 v178, v153, v153
	v_pk_mul_f32 v[124:125], v[124:125], v[178:179] op_sel_hi:[1,0]
	s_waitcnt lgkmcnt(1)
	v_add_f32_e32 v161, v161, v165
	v_add_f32_e32 v165, v173, v176
	s_waitcnt lgkmcnt(0)
	v_add_f32_e32 v149, v149, v174
	v_mul_f32_e32 v174, 0xbfb8aa3b, v153
	v_pk_mul_f32 v[180:181], v[128:129], v[174:175] op_sel_hi:[1,0]
	v_pk_mul_f32 v[176:177], v[126:127], v[174:175] op_sel_hi:[1,0]
	v_exp_f32_e32 v180, v180
	v_exp_f32_e32 v181, v181
	v_pk_mul_f32 v[128:129], v[118:119], v[174:175] op_sel_hi:[1,0]
	v_exp_f32_e32 v176, v176
	v_exp_f32_e32 v128, v128
	v_pk_add_f32 v[126:127], v[180:181], 1.0 op_sel_hi:[1,0]
	v_exp_f32_e32 v129, v129
	v_rcp_f32_e32 v126, v126
	v_rcp_f32_e32 v127, v127
	v_exp_f32_e32 v177, v177
	ds_bpermute_b32 v173, v151, v165
	v_fmamk_f32 v155, v155, 0x3a800000, v172
	v_pk_mul_f32 v[124:125], v[124:125], v[126:127]
	v_pk_add_f32 v[126:127], v[128:129], 1.0 op_sel_hi:[1,0]
	v_pk_mul_f32 v[128:129], v[120:121], v[174:175] op_sel_hi:[1,0]
	v_pk_add_f32 v[176:177], v[176:177], 1.0 op_sel_hi:[1,0]
	v_exp_f32_e32 v128, v128
	v_exp_f32_e32 v129, v129
	v_rcp_f32_e32 v126, v126
	v_rcp_f32_e32 v127, v127
	v_rcp_f32_e32 v176, v176
	v_pk_add_f32 v[118:119], v[128:129], 1.0 op_sel_hi:[1,0]
	v_rcp_f32_e32 v177, v177
	v_rcp_f32_e32 v118, v118
	v_rcp_f32_e32 v119, v119
	v_rsq_f32_e32 v155, v155
	v_pk_mul_f32 v[114:115], v[114:115], v[178:179] op_sel_hi:[1,0]
	v_pk_mul_f32 v[122:123], v[122:123], v[178:179] op_sel_hi:[1,0]
	v_pk_mul_f32 v[114:115], v[114:115], v[126:127]
	v_pk_mul_f32 v[116:117], v[116:117], v[178:179] op_sel_hi:[1,0]
	s_waitcnt lgkmcnt(0)
	v_add_f32_e32 v151, v165, v173
	v_ashrrev_i32_e32 v165, 31, v164
	v_pk_mul_f32 v[122:123], v[122:123], v[176:177]
	v_pk_mul_f32 v[116:117], v[116:117], v[118:119]
	v_cvt_pk_bf16_f32 v230, v122, v123
	v_cvt_pk_bf16_f32 v231, v124, v125
	v_cvt_pk_bf16_f32 v232, v114, v115
	v_mov_b64_e32 v[114:115], s[8:9]
	v_cvt_pk_bf16_f32 v233, v116, v117
	v_lshlrev_b64 v[116:117], 1, v[164:165]
	v_mul_f32_e32 v124, 0xbfb8aa3b, v155
	v_pk_mul_f32 v[122:123], v[112:113], v[124:125] op_sel_hi:[1,0]
	v_pk_mul_f32 v[126:127], v[110:111], v[124:125] op_sel_hi:[1,0]
	v_exp_f32_e32 v122, v122
	v_exp_f32_e32 v123, v123
	v_pk_mul_f32 v[112:113], v[102:103], v[124:125] op_sel_hi:[1,0]
	v_mul_f32_e32 v118, v155, v155
	v_exp_f32_e32 v112, v112
	v_pk_add_f32 v[110:111], v[122:123], 1.0 op_sel_hi:[1,0]
	v_exp_f32_e32 v113, v113
	v_rcp_f32_e32 v110, v110
	v_rcp_f32_e32 v111, v111
	v_pk_mul_f32 v[108:109], v[108:109], v[118:119] op_sel_hi:[1,0]
	v_exp_f32_e32 v126, v126
	v_exp_f32_e32 v127, v127
	v_pk_mul_f32 v[108:109], v[108:109], v[110:111]
	v_pk_add_f32 v[110:111], v[112:113], 1.0 op_sel_hi:[1,0]
	v_pk_mul_f32 v[112:113], v[104:105], v[124:125] op_sel_hi:[1,0]
	v_rcp_f32_e32 v110, v110
	v_exp_f32_e32 v112, v112
	v_exp_f32_e32 v113, v113
	v_rcp_f32_e32 v111, v111
	v_pk_add_f32 v[120:121], v[126:127], 1.0 op_sel_hi:[1,0]
	v_fmamk_f32 v157, v157, 0x3a800000, v172
	v_pk_add_f32 v[102:103], v[112:113], 1.0 op_sel_hi:[1,0]
	v_rcp_f32_e32 v120, v120
	v_rcp_f32_e32 v102, v102
	v_rcp_f32_e32 v103, v103
	v_rcp_f32_e32 v121, v121
	v_rsq_f32_e32 v157, v157
	v_pk_mul_f32 v[98:99], v[98:99], v[118:119] op_sel_hi:[1,0]
	v_pk_mul_f32 v[106:107], v[106:107], v[118:119] op_sel_hi:[1,0]
	v_pk_mul_f32 v[104:105], v[98:99], v[110:111]
	v_pk_mul_f32 v[98:99], v[100:101], v[118:119] op_sel_hi:[1,0]
	v_pk_mul_f32 v[106:107], v[106:107], v[120:121]
	v_pk_mul_f32 v[102:103], v[98:99], v[102:103]
	v_cvt_pk_bf16_f32 v234, v106, v107
	v_cvt_pk_bf16_f32 v235, v108, v109
	v_cvt_pk_bf16_f32 v236, v104, v105
	v_mul_f32_e32 v104, 0xbfb8aa3b, v157
	v_cvt_pk_bf16_f32 v237, v102, v103
	v_pk_mul_f32 v[102:103], v[96:97], v[104:105] op_sel_hi:[1,0]
	v_pk_mul_f32 v[106:107], v[94:95], v[104:105] op_sel_hi:[1,0]
	v_exp_f32_e32 v102, v102
	v_exp_f32_e32 v103, v103
	v_pk_mul_f32 v[96:97], v[86:87], v[104:105] op_sel_hi:[1,0]
	v_mul_f32_e32 v98, v157, v157
	v_exp_f32_e32 v96, v96
	v_pk_add_f32 v[94:95], v[102:103], 1.0 op_sel_hi:[1,0]
	v_exp_f32_e32 v97, v97
	v_rcp_f32_e32 v94, v94
	v_rcp_f32_e32 v95, v95
	v_pk_mul_f32 v[92:93], v[92:93], v[98:99] op_sel_hi:[1,0]
	v_exp_f32_e32 v106, v106
	v_exp_f32_e32 v107, v107
	v_pk_mul_f32 v[92:93], v[92:93], v[94:95]
	v_pk_add_f32 v[94:95], v[96:97], 1.0 op_sel_hi:[1,0]
	v_pk_mul_f32 v[96:97], v[88:89], v[104:105] op_sel_hi:[1,0]
	v_rcp_f32_e32 v94, v94
	v_exp_f32_e32 v96, v96
	v_exp_f32_e32 v97, v97
	v_rcp_f32_e32 v95, v95
	v_pk_add_f32 v[100:101], v[106:107], 1.0 op_sel_hi:[1,0]
	v_fmamk_f32 v159, v159, 0x3a800000, v172
	v_pk_add_f32 v[86:87], v[96:97], 1.0 op_sel_hi:[1,0]
	v_rcp_f32_e32 v100, v100
	v_rcp_f32_e32 v86, v86
	v_rcp_f32_e32 v87, v87
	v_rcp_f32_e32 v101, v101
	v_rsq_f32_e32 v159, v159
	v_pk_mul_f32 v[82:83], v[82:83], v[98:99] op_sel_hi:[1,0]
	v_pk_mul_f32 v[90:91], v[90:91], v[98:99] op_sel_hi:[1,0]
	v_pk_mul_f32 v[88:89], v[82:83], v[94:95]
	v_pk_mul_f32 v[82:83], v[84:85], v[98:99] op_sel_hi:[1,0]
	v_pk_mul_f32 v[90:91], v[90:91], v[100:101]
	v_pk_mul_f32 v[86:87], v[82:83], v[86:87]
	v_cvt_pk_bf16_f32 v238, v90, v91
	v_cvt_pk_bf16_f32 v239, v92, v93
	v_cvt_pk_bf16_f32 v240, v88, v89
	v_mul_f32_e32 v88, 0xbfb8aa3b, v159
	v_cvt_pk_bf16_f32 v241, v86, v87
	v_pk_mul_f32 v[86:87], v[80:81], v[88:89] op_sel_hi:[1,0]
; __device__ __forceinline__ unsigned cvt_pk_bf16(float lo, float hi) { unsigned r; asm volatile("v_cvt_pk_bf16_f32 %0, %1, %2" : "=v"(r) : "v"(lo), "v"(hi)); return r; }
;     __device__ __forceinline__ void operator()(const pg8::f32x4 (&acc)[2][2][4][2], const Unit& u, int wr, int wc, int fr, int fq) const {
;     ...
;             for (int m = 0; m < 4; ++m) { float r[8]; const float rs = rsv[ai * 4 + m]; const float c1 = -1.4426950408889634f * rs, rs2 = rs * rs;
; #pragma unroll
;                 for (int n = 0; n < 2; ++n)
; #pragma unroll
;                     for (int e = 0; e < 4; e += 2) { const f32x2 ag = {acc[ai][0][m][n][e], acc[ai][0][m][n][e + 1]}, au = {acc[ai][1][m][n][e], acc[ai][1][m][n][e + 1]};
;                         const f32x2 t = ag * c1; f32x2 d; d.x = __builtin_amdgcn_exp2f(t.x); d.y = __builtin_amdgcn_exp2f(t.y); d = d + 1.0f;
;                         f32x2 q; q.x = __builtin_amdgcn_rcpf(d.x); q.y = __builtin_amdgcn_rcpf(d.y); const f32x2 o = (ag * au) * rs2 * q; r[4 * n + e] = o.x; r[4 * n + e + 1] = o.y; }
;                 v4u w; w.x = cvt_pk_bf16(r[0], r[1]); w.y = cvt_pk_bf16(r[2], r[3]); w.z = cvt_pk_bf16(r[4], r[5]); w.w = cvt_pk_bf16(r[6], r[7]);
;                 __builtin_nontemporal_store(w, (v4u*)(O + (size_t)(row0 + ai * HALF + m * 16) * FF + col0)); }
	v_pk_mul_f32 v[90:91], v[78:79], v[88:89] op_sel_hi:[1,0]
	v_exp_f32_e32 v86, v86
	v_exp_f32_e32 v87, v87
	v_pk_mul_f32 v[80:81], v[70:71], v[88:89] op_sel_hi:[1,0]
	v_mul_f32_e32 v82, v159, v159
	v_exp_f32_e32 v80, v80
	v_pk_add_f32 v[78:79], v[86:87], 1.0 op_sel_hi:[1,0]
	v_exp_f32_e32 v81, v81
	v_rcp_f32_e32 v78, v78
	v_rcp_f32_e32 v79, v79
	v_pk_mul_f32 v[76:77], v[76:77], v[82:83] op_sel_hi:[1,0]
	v_exp_f32_e32 v90, v90
	v_exp_f32_e32 v91, v91
	v_pk_mul_f32 v[76:77], v[76:77], v[78:79]
	v_pk_add_f32 v[78:79], v[80:81], 1.0 op_sel_hi:[1,0]
	v_pk_mul_f32 v[80:81], v[72:73], v[88:89] op_sel_hi:[1,0]
	v_rcp_f32_e32 v78, v78
	v_exp_f32_e32 v80, v80
	v_exp_f32_e32 v81, v81
	v_rcp_f32_e32 v79, v79
	v_pk_add_f32 v[84:85], v[90:91], 1.0 op_sel_hi:[1,0]
	v_fmamk_f32 v163, v163, 0x3a800000, v172
	v_pk_add_f32 v[70:71], v[80:81], 1.0 op_sel_hi:[1,0]
	v_rcp_f32_e32 v84, v84
	v_rcp_f32_e32 v70, v70
	v_rcp_f32_e32 v71, v71
	v_rcp_f32_e32 v85, v85
	v_rsq_f32_e32 v163, v163
	v_pk_mul_f32 v[66:67], v[66:67], v[82:83] op_sel_hi:[1,0]
	v_pk_mul_f32 v[74:75], v[74:75], v[82:83] op_sel_hi:[1,0]
	v_pk_mul_f32 v[72:73], v[66:67], v[78:79]
	v_pk_mul_f32 v[66:67], v[68:69], v[82:83] op_sel_hi:[1,0]
	v_pk_mul_f32 v[74:75], v[74:75], v[84:85]
	v_pk_mul_f32 v[70:71], v[66:67], v[70:71]
	v_cvt_pk_bf16_f32 v242, v74, v75
	v_cvt_pk_bf16_f32 v243, v76, v77
	v_cvt_pk_bf16_f32 v244, v72, v73
	v_mul_f32_e32 v72, 0xbfb8aa3b, v163
	v_cvt_pk_bf16_f32 v245, v70, v71
	v_pk_mul_f32 v[70:71], v[64:65], v[72:73] op_sel_hi:[1,0]
	v_pk_mul_f32 v[74:75], v[62:63], v[72:73] op_sel_hi:[1,0]
	v_exp_f32_e32 v70, v70
	v_exp_f32_e32 v71, v71
	v_pk_mul_f32 v[64:65], v[54:55], v[72:73] op_sel_hi:[1,0]
	v_mul_f32_e32 v66, v163, v163
	v_exp_f32_e32 v64, v64
	v_pk_add_f32 v[62:63], v[70:71], 1.0 op_sel_hi:[1,0]
	v_exp_f32_e32 v65, v65
	v_rcp_f32_e32 v62, v62
	v_rcp_f32_e32 v63, v63
	v_pk_mul_f32 v[60:61], v[60:61], v[66:67] op_sel_hi:[1,0]
	v_exp_f32_e32 v74, v74
	v_exp_f32_e32 v75, v75
	v_pk_mul_f32 v[60:61], v[60:61], v[62:63]
	v_pk_add_f32 v[62:63], v[64:65], 1.0 op_sel_hi:[1,0]
	v_pk_mul_f32 v[64:65], v[56:57], v[72:73] op_sel_hi:[1,0]
	v_rcp_f32_e32 v62, v62
	v_exp_f32_e32 v64, v64
	v_exp_f32_e32 v65, v65
	v_rcp_f32_e32 v63, v63
	v_pk_add_f32 v[68:69], v[74:75], 1.0 op_sel_hi:[1,0]
	v_fmamk_f32 v161, v161, 0x3a800000, v172
	v_pk_add_f32 v[54:55], v[64:65], 1.0 op_sel_hi:[1,0]
	v_rcp_f32_e32 v68, v68
	v_rcp_f32_e32 v54, v54
	v_rcp_f32_e32 v55, v55
	v_rcp_f32_e32 v69, v69
	v_rsq_f32_e32 v161, v161
	v_pk_mul_f32 v[50:51], v[50:51], v[66:67] op_sel_hi:[1,0]
	v_pk_mul_f32 v[58:59], v[58:59], v[66:67] op_sel_hi:[1,0]
	v_pk_mul_f32 v[56:57], v[50:51], v[62:63]
	v_pk_mul_f32 v[50:51], v[52:53], v[66:67] op_sel_hi:[1,0]
	v_pk_mul_f32 v[58:59], v[58:59], v[68:69]
	v_pk_mul_f32 v[54:55], v[50:51], v[54:55]
	v_cvt_pk_bf16_f32 v246, v58, v59
	v_cvt_pk_bf16_f32 v247, v60, v61
	v_cvt_pk_bf16_f32 v248, v56, v57
	v_mul_f32_e32 v56, 0xbfb8aa3b, v161
	v_cvt_pk_bf16_f32 v249, v54, v55
	v_pk_mul_f32 v[54:55], v[48:49], v[56:57] op_sel_hi:[1,0]
	v_pk_mul_f32 v[58:59], v[46:47], v[56:57] op_sel_hi:[1,0]
	v_exp_f32_e32 v54, v54
	v_exp_f32_e32 v55, v55
	v_pk_mul_f32 v[48:49], v[38:39], v[56:57] op_sel_hi:[1,0]
	v_mul_f32_e32 v50, v161, v161
	v_exp_f32_e32 v48, v48
	v_pk_add_f32 v[46:47], v[54:55], 1.0 op_sel_hi:[1,0]
	v_exp_f32_e32 v49, v49
	v_rcp_f32_e32 v46, v46
	v_rcp_f32_e32 v47, v47
	v_pk_mul_f32 v[44:45], v[44:45], v[50:51] op_sel_hi:[1,0]
	v_exp_f32_e32 v58, v58
	v_exp_f32_e32 v59, v59
	v_pk_mul_f32 v[44:45], v[44:45], v[46:47]
	v_pk_add_f32 v[46:47], v[48:49], 1.0 op_sel_hi:[1,0]
	v_pk_mul_f32 v[48:49], v[40:41], v[56:57] op_sel_hi:[1,0]
	v_rcp_f32_e32 v46, v46
	v_exp_f32_e32 v48, v48
	v_exp_f32_e32 v49, v49
	v_rcp_f32_e32 v47, v47
	v_pk_add_f32 v[52:53], v[58:59], 1.0 op_sel_hi:[1,0]
	v_fmamk_f32 v151, v151, 0x3a800000, v172
	v_pk_add_f32 v[38:39], v[48:49], 1.0 op_sel_hi:[1,0]
	v_rcp_f32_e32 v52, v52
	v_rcp_f32_e32 v38, v38
	v_rcp_f32_e32 v39, v39
	v_rcp_f32_e32 v53, v53
	v_rsq_f32_e32 v151, v151
	v_pk_mul_f32 v[34:35], v[34:35], v[50:51] op_sel_hi:[1,0]
	v_pk_mul_f32 v[42:43], v[42:43], v[50:51] op_sel_hi:[1,0]
	v_pk_mul_f32 v[40:41], v[34:35], v[46:47]
	v_pk_mul_f32 v[34:35], v[36:37], v[50:51] op_sel_hi:[1,0]
	v_pk_mul_f32 v[42:43], v[42:43], v[52:53]
	v_pk_mul_f32 v[38:39], v[34:35], v[38:39]
	v_cvt_pk_bf16_f32 v250, v42, v43
	v_cvt_pk_bf16_f32 v251, v44, v45
; __device__ __forceinline__ unsigned cvt_pk_bf16(float lo, float hi) { unsigned r; asm volatile("v_cvt_pk_bf16_f32 %0, %1, %2" : "=v"(r) : "v"(lo), "v"(hi)); return r; }
; #define PG8_BAR __builtin_amdgcn_s_barrier()
; template <class Epi, class Sched, bool ALIGN_EPI = false, bool SP2 = false>
; __device__ __forceinline__ void gemm_phase(PG8_LAS unsigned char* lds, const Gemm g, const Sched& S, const Epi& E) {
;     ...
;         if constexpr (ALIGN_EPI) { if (wr == 0) PG8_BAR; }
;         if constexpr (!Epi::AFTER_DRAIN) { E(acc, cur, wr, wc, fr, fq); S.done(cur); }
;         if (!has_next) break;
;     __device__ __forceinline__ void operator()(const pg8::f32x4 (&acc)[2][2][4][2], const Unit& u, int wr, int wc, int fr, int fq) const {
;     ...
;             for (int m = 0; m < 4; ++m) { float r[8]; const float rs = rsv[ai * 4 + m]; const float c1 = -1.4426950408889634f * rs, rs2 = rs * rs;
; #pragma unroll
;                 for (int n = 0; n < 2; ++n)
; #pragma unroll
;                     for (int e = 0; e < 4; e += 2) { const f32x2 ag = {acc[ai][0][m][n][e], acc[ai][0][m][n][e + 1]}, au = {acc[ai][1][m][n][e], acc[ai][1][m][n][e + 1]};
;                         const f32x2 t = ag * c1; f32x2 d; d.x = __builtin_amdgcn_exp2f(t.x); d.y = __builtin_amdgcn_exp2f(t.y); d = d + 1.0f;
;                         f32x2 q; q.x = __builtin_amdgcn_rcpf(d.x); q.y = __builtin_amdgcn_rcpf(d.y); const f32x2 o = (ag * au) * rs2 * q; r[4 * n + e] = o.x; r[4 * n + e + 1] = o.y; }
;                 v4u w; w.x = cvt_pk_bf16(r[0], r[1]); w.y = cvt_pk_bf16(r[2], r[3]); w.z = cvt_pk_bf16(r[4], r[5]); w.w = cvt_pk_bf16(r[6], r[7]);
;                 __builtin_nontemporal_store(w, (v4u*)(O + (size_t)(row0 + ai * HALF + m * 16) * FF + col0)); }
	v_cvt_pk_bf16_f32 v252, v40, v41
	v_mul_f32_e32 v40, 0xbfb8aa3b, v151
	v_cvt_pk_bf16_f32 v253, v38, v39
	v_pk_mul_f32 v[38:39], v[32:33], v[40:41] op_sel_hi:[1,0]
	v_pk_mul_f32 v[42:43], v[30:31], v[40:41] op_sel_hi:[1,0]
	v_exp_f32_e32 v38, v38
	v_exp_f32_e32 v39, v39
	v_pk_mul_f32 v[32:33], v[22:23], v[40:41] op_sel_hi:[1,0]
	v_mul_f32_e32 v34, v151, v151
	v_exp_f32_e32 v32, v32
	v_pk_add_f32 v[30:31], v[38:39], 1.0 op_sel_hi:[1,0]
	v_exp_f32_e32 v33, v33
	v_rcp_f32_e32 v30, v30
	v_rcp_f32_e32 v31, v31
	v_pk_mul_f32 v[28:29], v[28:29], v[34:35] op_sel_hi:[1,0]
	v_exp_f32_e32 v42, v42
	v_exp_f32_e32 v43, v43
	v_pk_mul_f32 v[28:29], v[28:29], v[30:31]
	v_pk_add_f32 v[30:31], v[32:33], 1.0 op_sel_hi:[1,0]
	v_pk_mul_f32 v[32:33], v[24:25], v[40:41] op_sel_hi:[1,0]
	v_rcp_f32_e32 v30, v30
	v_exp_f32_e32 v32, v32
	v_exp_f32_e32 v33, v33
	v_rcp_f32_e32 v31, v31
	v_pk_add_f32 v[36:37], v[42:43], 1.0 op_sel_hi:[1,0]
	v_fmamk_f32 v149, v149, 0x3a800000, v172
	v_pk_add_f32 v[22:23], v[32:33], 1.0 op_sel_hi:[1,0]
	v_rcp_f32_e32 v36, v36
	v_rcp_f32_e32 v22, v22
	v_rcp_f32_e32 v23, v23
	v_rcp_f32_e32 v37, v37
	v_rsq_f32_e32 v149, v149
	v_pk_mul_f32 v[18:19], v[18:19], v[34:35] op_sel_hi:[1,0]
	v_pk_mul_f32 v[26:27], v[26:27], v[34:35] op_sel_hi:[1,0]
	v_pk_mul_f32 v[24:25], v[18:19], v[30:31]
	v_pk_mul_f32 v[18:19], v[20:21], v[34:35] op_sel_hi:[1,0]
	v_pk_mul_f32 v[26:27], v[26:27], v[36:37]
	v_pk_mul_f32 v[22:23], v[18:19], v[22:23]
	v_cvt_pk_bf16_f32 v144, v26, v27
	v_cvt_pk_bf16_f32 v145, v28, v29
	v_cvt_pk_bf16_f32 v146, v24, v25
	v_mul_f32_e32 v24, 0xbfb8aa3b, v149
	v_cvt_pk_bf16_f32 v147, v22, v23
	v_pk_mul_f32 v[22:23], v[16:17], v[24:25] op_sel_hi:[1,0]
	v_pk_mul_f32 v[26:27], v[14:15], v[24:25] op_sel_hi:[1,0]
	v_exp_f32_e32 v22, v22
	v_exp_f32_e32 v23, v23
	v_pk_mul_f32 v[16:17], v[6:7], v[24:25] op_sel_hi:[1,0]
	v_mul_f32_e32 v18, v149, v149
	v_exp_f32_e32 v16, v16
	v_pk_add_f32 v[14:15], v[22:23], 1.0 op_sel_hi:[1,0]
	v_exp_f32_e32 v17, v17
	v_rcp_f32_e32 v14, v14
	v_rcp_f32_e32 v15, v15
	v_pk_mul_f32 v[12:13], v[12:13], v[18:19] op_sel_hi:[1,0]
	v_exp_f32_e32 v26, v26
	v_exp_f32_e32 v27, v27
	v_pk_mul_f32 v[12:13], v[12:13], v[14:15]
	v_pk_add_f32 v[14:15], v[16:17], 1.0 op_sel_hi:[1,0]
	v_pk_mul_f32 v[16:17], v[8:9], v[24:25] op_sel_hi:[1,0]
	v_rcp_f32_e32 v14, v14
	v_exp_f32_e32 v16, v16
	v_exp_f32_e32 v17, v17
	v_rcp_f32_e32 v15, v15
	v_pk_add_f32 v[20:21], v[26:27], 1.0 op_sel_hi:[1,0]
	v_pk_mul_f32 v[2:3], v[2:3], v[18:19] op_sel_hi:[1,0]
	v_pk_add_f32 v[6:7], v[16:17], 1.0 op_sel_hi:[1,0]
	v_rcp_f32_e32 v20, v20
	v_rcp_f32_e32 v6, v6
	v_rcp_f32_e32 v7, v7
	v_rcp_f32_e32 v21, v21
	v_pk_mul_f32 v[8:9], v[2:3], v[14:15]
	v_pk_mul_f32 v[2:3], v[4:5], v[18:19] op_sel_hi:[1,0]
	v_pk_mul_f32 v[10:11], v[10:11], v[18:19] op_sel_hi:[1,0]
	v_pk_mul_f32 v[6:7], v[2:3], v[6:7]
	v_pk_mul_f32 v[10:11], v[10:11], v[20:21]
	s_nop 0
	v_cvt_pk_bf16_f32 v2, v10, v11
	v_cvt_pk_bf16_f32 v3, v12, v13
	v_cvt_pk_bf16_f32 v4, v8, v9
	v_cvt_pk_bf16_f32 v5, v6, v7
	v_lshlrev_b32_e32 v6, 4, v171
	v_add_u32_e32 v6, s23, v6
	v_add_u32_e32 v6, 0x20100, v6
	ds_write_b128 v6, v[2:5]
	s_mul_i32 s98, s22, 0x160000
	s_lshl_b32 s100, s45, 8
	s_add_u32 s98, s98, s100
	s_add_u32 s98, s98, s8
	s_addc_u32 s99, s9, 0
	s_cbranch_vccnz .LBB0_687
	s_andn2_b64 vcc, exec, s[4:5]
	s_cbranch_vccnz .LBB0_686
	s_barrier
	s_branch .LBB0_686
.LBB0_697:
	s_cmp_eq_u32 s99, 0
	s_cbranch_scc1 .Ld7f_skip_0
	v_lshlrev_b32_e32 v6, 4, v171
	v_add_u32_e32 v6, s23, v6
	v_add_u32_e32 v6, 0x20100, v6
	ds_read_b128 v[2:5], v6
	global_store_dwordx4 v255, v[230:233], s[98:99] nt
	s_add_u32 s100, s98, 0x16000
	s_addc_u32 s101, s99, 0
	global_store_dwordx4 v255, v[234:237], s[100:101] nt
	s_add_u32 s100, s98, 0x2c000
	s_addc_u32 s101, s99, 0
	global_store_dwordx4 v255, v[238:241], s[100:101] nt
	s_add_u32 s100, s98, 0x42000
	s_addc_u32 s101, s99, 0
	global_store_dwordx4 v255, v[242:245], s[100:101] nt
	s_add_u32 s100, s98, 0xb0000
	s_addc_u32 s101, s99, 0
	global_store_dwordx4 v255, v[246:249], s[100:101] nt
	s_add_u32 s100, s98, 0xc6000
	s_addc_u32 s101, s99, 0
	global_store_dwordx4 v255, v[250:253], s[100:101] nt
	s_add_u32 s100, s98, 0xdc000
	s_addc_u32 s101, s99, 0
	global_store_dwordx4 v255, v[144:147], s[100:101] nt
	s_waitcnt lgkmcnt(0)
	s_add_u32 s100, s98, 0xf2000
	s_addc_u32 s101, s99, 0
	global_store_dwordx4 v255, v[2:5], s[100:101] nt
	s_mov_b32 s99, 0

; #define PG8_STAGE(bufoff, gbase, voff) do { _Pragma("unroll") for (int _i = 0; _i < 2; ++_i) \
;         __builtin_amdgcn_global_load_lds((const unsigned*)((const char*)(gbase) + (voff)[_i]), (PG8_LAS unsigned*)(lds + (bufoff) + ldsw + _i * 8192), 16, 0, 0); } while (0)
; #define PG8_WAIT_V(n) asm volatile("s_waitcnt vmcnt(" #n ")" ::: "memory")
; #define PG8_BAR __builtin_amdgcn_s_barrier()
; template <class Epi, class Sched, bool ALIGN_EPI = false, bool SP2 = false>
; __device__ __forceinline__ void gemm_phase(PG8_LAS unsigned char* lds, const Gemm g, const Sched& S, const Epi& E) {
;     ...
;         PG8_STAGE(PG8_SB(0, 0), cB, voffB); PG8_STAGE(PG8_SB(0, 1), cB + hstepB, voffB); PG8_STAGE(PG8_SA(0, 0), cA, voffA); PG8_STAGE(PG8_SA(0, 1), cA + hstepA, voffA);
;         if (wr == 1) PG8_BAR;
;         PG8_WAIT_V(2); PG8_BAR;
;         PG8_STAGE(PG8_SB(1, 0), cB + kstep, voffB); PG8_STAGE(PG8_SA(1, 0), cA + kstep, voffA); PG8_STAGE(PG8_SB(1, 1), cB + hstepB + kstep, voffB);
;         PG8_WAIT_V(6); PG8_BAR;
;     __device__ __forceinline__ void operator()(const pg8::f32x4 (&acc)[2][2][4][2], const Unit& u, int wr, int wc, int fr, int fq) const {
;         const int row0 = u.pm * BM + wr * 64 + fr, col0 = u.pn * HALF + wc * 32 + 8 * fq;
;         float rsv[8]; rstd8(ss, row0, fq, rsv);
.LBB0_1547:
	s_add_u32 s8, s78, 0x13c00000
	s_addc_u32 s9, s79, 0
	s_lshl_b32 s10, s10, 5
	s_and_b32 s16, s10, 0x60
	s_mov_b64 s[10:11], 0x80
	s_add_i32 m0, s23, 0x18000
	v_lshl_add_u64 v[8:9], v[8:9], 0, s[10:11]
	s_lshl_b32 s13, s12, 13
	s_lshl_b32 s17, s16, 7
	s_waitcnt vmcnt(2)
	s_barrier
	global_load_lds_dwordx4 v[8:9], off
	v_lshl_add_u64 v[6:7], v[6:7], 0, s[10:11]
	s_add_i32 m0, s23, 0x1a000
	s_add_i32 s38, s23, 0x8000
	s_add_i32 s39, s23, 0xa000
	global_load_lds_dwordx4 v[6:7], off
	v_lshl_add_u64 v[2:3], v[2:3], 0, s[10:11]
	s_mov_b32 m0, s38
	s_add_u32 s14, s26, 0x40080
	global_load_lds_dwordx4 v[2:3], off
	v_lshl_add_u64 v[2:3], v[4:5], 0, s[10:11]
	s_mov_b32 m0, s39
	s_addc_u32 s15, s27, 0
	global_load_lds_dwordx4 v[2:3], off
	s_add_i32 m0, s23, 0x1c000
	v_lshl_add_u64 v[2:3], s[14:15], 0, v[134:135]
	global_load_lds_dwordx4 v[2:3], off
	v_lshl_add_u64 v[2:3], s[14:15], 0, v[130:131]
	s_add_i32 m0, s23, 0x1e000
	v_bfe_u32 v4, v12, 4, 2
	global_load_lds_dwordx4 v[2:3], off
	v_and_b32_e32 v3, 15, v12
	v_lshlrev_b32_e32 v2, 4, v4
	v_lshlrev_b32_e32 v5, 2, v12
	v_lshl_or_b32 v1, s12, 6, v3
	v_lshl_or_b32 v3, v3, 6, v2
	v_and_b32_e32 v5, 32, v5
	v_bitop3_b32 v6, v3, s13, v5 bitop3:0xde
	v_bitop3_b32 v166, v3, s17, v5 bitop3:0xde
	v_mov_b32_e32 v3, v135
	s_sext_i32_i8 s45, s6
	s_cmpk_lt_u32 s7, 0x100
	v_lshl_add_u64 v[2:3], s[78:79], 0, v[2:3]
	s_mov_b64 s[6:7], 0x5800000
	v_lshl_add_u64 v[138:139], v[2:3], 0, s[6:7]
	v_lshlrev_b32_e32 v2, 14, v15
	v_and_b32_e32 v2, 0xffff8000, v2
	v_lshl_add_u32 v2, v14, 11, v2
	v_and_b32_e32 v3, 1, v15
	v_lshl_or_b32 v2, v3, 6, v2
	v_lshl_add_u32 v140, v16, 1, v2
	v_lshlrev_b32_e32 v2, 14, v10
	v_and_b32_e32 v2, 0xffff8000, v2
	v_lshl_add_u32 v2, v11, 11, v2
	v_and_b32_e32 v3, 1, v10
	s_waitcnt vmcnt(6)
	v_lshl_or_b32 v2, v3, 6, v2
	s_cselect_b64 s[12:13], -1, 0
	v_lshl_add_u32 v142, v13, 1, v2
	s_add_i32 s42, 0, 0x10000
	s_add_i32 s43, 0, 0x14000
	v_mbcnt_lo_u32_b32 v2, -1, 0
	s_ashr_i32 s40, s82, 31
	s_mov_b32 s41, s82
	v_lshl_or_b32 v167, v4, 3, s16
	v_mul_u32_u24_e32 v255, 0x1600, v1
	v_lshl_add_u32 v255, v167, 1, v255
	s_mov_b32 s99, 0
	v_mov_b32_e32 v141, v135
	v_mov_b32_e32 v143, v135
	v_add_u32_e32 v168, s42, v166
	v_add_u32_e32 v169, s43, v166
	v_add_u32_e32 v170, 0, v6
	v_mbcnt_hi_u32_b32 v171, -1, v2
	v_mov_b32_e32 v172, 0x358637bd
	s_movk_i32 s44, 0x1600
	s_barrier
	s_branch .LBB0_1550

; __global__ void __launch_bounds__(NTHR, 2) hybrid_fwd(Args args) {
	.amdhsa_kernel _Z10hybrid_fwd4Args
		.amdhsa_group_segment_fixed_size 0
		.amdhsa_private_segment_fixed_size 0
		.amdhsa_kernarg_size 512
		.amdhsa_user_sgpr_count 2
		.amdhsa_user_sgpr_dispatch_ptr 0
		.amdhsa_user_sgpr_queue_ptr 0
		.amdhsa_user_sgpr_kernarg_segment_ptr 1
		.amdhsa_user_sgpr_dispatch_id 0
		.amdhsa_user_sgpr_kernarg_preload_length 0
		.amdhsa_user_sgpr_kernarg_preload_offset 0
		.amdhsa_user_sgpr_private_segment_size 0
		.amdhsa_uses_dynamic_stack 0
		.amdhsa_enable_private_segment 0
		.amdhsa_system_sgpr_workgroup_id_x 1
		.amdhsa_system_sgpr_workgroup_id_y 0
		.amdhsa_system_sgpr_workgroup_id_z 0
		.amdhsa_system_sgpr_workgroup_info 0
		.amdhsa_system_vgpr_workitem_id 0
		.amdhsa_next_free_vgpr 256
		.amdhsa_next_free_sgpr 102
		.amdhsa_accum_offset 256
		.amdhsa_reserve_vcc 1
		.amdhsa_float_round_mode_32 0
		.amdhsa_float_round_mode_16_64 0
		.amdhsa_float_denorm_mode_32 3
		.amdhsa_float_denorm_mode_16_64 3
		.amdhsa_dx10_clamp 1
		.amdhsa_ieee_mode 1
		.amdhsa_fp16_overflow 0
		.amdhsa_tg_split 0
		.amdhsa_exception_fp_ieee_invalid_op 0
		.amdhsa_exception_fp_denorm_src 0
		.amdhsa_exception_fp_ieee_div_zero 0
		.amdhsa_exception_fp_ieee_overflow 0
		.amdhsa_exception_fp_ieee_underflow 0
		.amdhsa_exception_fp_ieee_inexact 0
		.amdhsa_exception_int_div_zero 0
	.end_amdhsa_kernel

; __global__ void __launch_bounds__(NTHR, 2) hybrid_fwd(Args args) {
amdhsa.kernels:
  - .agpr_count:     0
    .args:
      - .offset:         0
        .size:           256
        .value_kind:     by_value
      - .offset:         256
        .size:           4
        .value_kind:     hidden_block_count_x
      - .offset:         260
        .size:           4
        .value_kind:     hidden_block_count_y
      - .offset:         264
        .size:           4
        .value_kind:     hidden_block_count_z
      - .offset:         268
        .size:           2
        .value_kind:     hidden_group_size_x
      - .offset:         270
        .size:           2
        .value_kind:     hidden_group_size_y
      - .offset:         272
        .size:           2
        .value_kind:     hidden_group_size_z
      - .offset:         274
        .size:           2
        .value_kind:     hidden_remainder_x
      - .offset:         276
        .size:           2
        .value_kind:     hidden_remainder_y
      - .offset:         278
        .size:           2
        .value_kind:     hidden_remainder_z
      - .offset:         296
        .size:           8
        .value_kind:     hidden_global_offset_x
      - .offset:         304
        .size:           8
        .value_kind:     hidden_global_offset_y
      - .offset:         312
        .size:           8
        .value_kind:     hidden_global_offset_z
      - .offset:         320
        .size:           2
        .value_kind:     hidden_grid_dims
      - .offset:         376
        .size:           4
        .value_kind:     hidden_dynamic_lds_size
    .group_segment_fixed_size: 0
    .kernarg_segment_align: 8
    .kernarg_segment_size: 512
    .language:       OpenCL C
    .language_version:
      - 2
      - 0
    .max_flat_workgroup_size: 512
    .name:           _Z10hybrid_fwd4Args
    .private_segment_fixed_size: 0
    .sgpr_count:     108
    .sgpr_spill_count: 29
    .symbol:         _Z10hybrid_fwd4Args.kd
    .uniform_work_group_size: 1
    .uses_dynamic_stack: false
    .vgpr_count:     256
    .vgpr_spill_count: 0
    .wavefront_size: 64
